# group-local 4-WG barriers for PA->PB, PE->PF, PF->PA (row remap), register-only weight transposes, pipelined adaLN GEMV
# baseline (speedup 1.0000x reference)
.LBB0_8:
	s_nop 0
	v_readlane_b32 s4, v255, 2
	v_readlane_b32 s6, v255, 4
	s_cmp_lt_i32 s6, 1
	v_readlane_b32 s7, v255, 5
	s_cselect_b64 s[22:23], -1, 0
	s_cmp_gt_i32 s6, 0
	v_readlane_b32 s5, v255, 3
	s_cselect_b64 s[2:3], -1, 0
	s_cmp_lt_i32 s7, 1
	s_cselect_b64 s[4:5], -1, 0
	s_or_b64 s[2:3], s[2:3], s[4:5]
	s_and_b64 vcc, exec, s[2:3]
	s_cbranch_vccnz .LBB0_219
	s_mov_b64 s[24:25], s[0:1]
	s_mov_b32 s26, s12
	s_mov_b32 s28, s13
	v_mov_b32_e32 v44, v220
	s_nop 0
	v_readfirstlane_b32 s2, v44
	s_ashr_i32 s27, s2, 6
	s_lshl_b32 s2, s26, 3
	v_and_b32_e32 v46, 63, v44
	s_add_i32 s29, s27, s2
	s_cmp_gt_i32 s29, 0xd7ff
	v_lshlrev_b32_e32 v13, 3, v46
	s_cbranch_scc1 .LBB0_58
	s_lshl_b32 s30, s28, 3
	s_load_dwordx2 s[2:3], s[24:25], 0x68
	s_load_dwordx2 s[4:5], s[24:25], 0xd0
	s_load_dwordx2 s[6:7], s[24:25], 0xc0
	s_load_dwordx2 s[8:9], s[24:25], 0xe8
	v_lshrrev_b32_e32 v0, 3, v46
	v_and_b32_e32 v1, 7, v46
	v_lshlrev_b32_e32 v2, 4, v1
	v_lshlrev_b32_e32 v3, 3, v0
	v_lshlrev_b32_e32 v4, 2, v1
	v_lshlrev_b32_e32 v5, 4, v0
	s_waitcnt lgkmcnt(0)
	s_mov_b32 s11, s29
	s_cmp_ge_u32 s11, 0x6c00
	s_cselect_b32 s16, 0x6c00, 0
	s_cselect_b32 s10, 2, 0
	s_sub_u32 s11, s11, s16
	s_cmp_ge_u32 s11, 0x3600
	s_cselect_b32 s16, 0x3600, 0
	s_cselect_b32 s17, 1, 0
	s_sub_u32 s11, s11, s16
	s_add_u32 s10, s10, s17
	s_cmp_lt_u32 s11, 0x2400
	s_cbranch_scc1 .Ltr_in1
	s_cmp_lt_u32 s11, 0x3400
	s_cbranch_scc1 .Ltr_out1
	s_sub_u32 s11, s11, 0x3400
	s_lshr_b32 s16, s11, 5
	s_and_b32 s17, s11, 31
	s_movk_i32 s14, 0x2000
	s_movk_i32 s15, 0x800
	s_mov_b32 s34, 0x10000
	s_lshl_b32 s31, s10, 23
	s_lshl_b32 s11, s16, 19
	s_add_u32 s31, s31, s11
	s_lshl_b32 s11, s17, 8
	s_add_u32 s31, s31, s11
	s_add_u32 s31, s6, s31
	s_addc_u32 s11, s7, 0
	s_bfe_u32 s14, s17, 0x30001
	s_lshl_b32 s14, s14, 8
	s_lshr_b32 s15, s17, 4
	s_lshl_b32 s15, s15, 7
	s_add_u32 s14, s14, s15
	s_and_b32 s15, s17, 1
	s_lshl_b32 s15, s15, 6
	s_add_u32 s14, s14, s15
	s_lshl_b32 s14, s14, 11
	s_lshl_b32 s15, s16, 7
	s_add_u32 s14, s14, s15
	s_lshl_b32 s15, s10, 22
	s_add_u32 s14, s14, s15
	s_add_u32 s17, s14, 0xae00000
	s_mov_b32 s16, s31
	s_mov_b32 s31, s17
	s_mov_b32 s17, s11
	s_movk_i32 s14, 0x2000
	s_movk_i32 s15, 0x800
	s_branch .Ltr_dec1
.Ltr_in1:
	s_mul_hi_u32 s16, s11, 0x38e38e39
	s_lshr_b32 s16, s16, 5
	s_mul_i32 s17, s16, 0x90
	s_sub_u32 s17, s11, s17
	s_mov_b32 s34, 0x40000
	s_mul_i32 s31, s10, 0x9000000
	s_mul_i32 s11, s16, 0x240000
	s_add_u32 s31, s31, s11
	s_lshl_b32 s11, s17, 8
	s_add_u32 s31, s31, s11
	s_add_u32 s14, s2, s31
	s_addc_u32 s15, s3, 0
	s_mul_i32 s31, s10, 0x4800000
	s_lshl_b32 s11, s17, 19
	s_add_u32 s31, s31, s11
	s_lshl_b32 s11, s16, 7
	s_add_u32 s31, s31, s11
	s_add_u32 s31, s31, 0x14600000
	s_mov_b32 s16, s14
	s_mov_b32 s17, s15
	s_mov_b32 s14, 0x9000
	s_movk_i32 s15, 0x2000
	s_branch .Ltr_dec1
.Ltr_out1:
	s_sub_u32 s11, s11, 0x2400
	s_lshr_b32 s16, s11, 6
	s_and_b32 s17, s11, 63
	s_mov_b32 s34, 0x40000
	s_lshl_b32 s31, s10, 26
	s_lshl_b32 s11, s16, 20
	s_add_u32 s31, s31, s11
	s_lshl_b32 s11, s17, 8
	s_add_u32 s31, s31, s11
	s_add_u32 s14, s4, s31
	s_addc_u32 s15, s5, 0
	s_lshl_b32 s31, s10, 25
	s_lshl_b32 s11, s17, 19
	s_add_u32 s31, s31, s11
	s_lshl_b32 s11, s16, 7
	s_add_u32 s31, s31, s11
	s_add_u32 s31, s31, 0xc600000
	s_mov_b32 s16, s14
	s_mov_b32 s17, s15
	s_movk_i32 s14, 0x4000
	s_movk_i32 s15, 0x2000
.Ltr_dec1:
	s_add_u32 s18, s8, s31
	s_addc_u32 s19, s9, 0
	v_mad_u32_u24 v16, v3, s14, v2
	v_add_u32_e32 v17, s14, v16
	v_add_u32_e32 v18, s14, v17
	v_add_u32_e32 v19, s14, v18
	v_add_u32_e32 v20, s14, v19
	v_add_u32_e32 v21, s14, v20
	v_add_u32_e32 v22, s14, v21
	v_add_u32_e32 v23, s14, v22
	v_mad_u32_u24 v24, v4, s15, v5
	v_add_u32_e32 v25, s15, v24
	v_add_u32_e32 v26, s15, v25
	v_add_u32_e32 v27, s15, v26
	global_load_dwordx4 v[64:67], v16, s[16:17] nt
	global_load_dwordx4 v[68:71], v17, s[16:17] nt
	global_load_dwordx4 v[72:75], v18, s[16:17] nt
	global_load_dwordx4 v[76:79], v19, s[16:17] nt
	global_load_dwordx4 v[80:83], v20, s[16:17] nt
	global_load_dwordx4 v[84:87], v21, s[16:17] nt
	global_load_dwordx4 v[88:91], v22, s[16:17] nt
	global_load_dwordx4 v[92:95], v23, s[16:17] nt
	global_load_dwordx4 v[96:99], v16, s[16:17] offset:128 nt
	global_load_dwordx4 v[100:103], v17, s[16:17] offset:128 nt
	global_load_dwordx4 v[104:107], v18, s[16:17] offset:128 nt
	global_load_dwordx4 v[108:111], v19, s[16:17] offset:128 nt
	global_load_dwordx4 v[112:115], v20, s[16:17] offset:128 nt
	global_load_dwordx4 v[116:119], v21, s[16:17] offset:128 nt
	global_load_dwordx4 v[120:123], v22, s[16:17] offset:128 nt
	global_load_dwordx4 v[124:127], v23, s[16:17] offset:128 nt
.Ltr_loop:
	s_add_u32 s29, s29, s30
	s_cmp_gt_u32 s29, 0xd7ff
	s_cbranch_scc1 .Ltr_lastA
	s_mov_b32 s11, s29
	s_cmp_ge_u32 s11, 0x6c00
	s_cselect_b32 s16, 0x6c00, 0
	s_cselect_b32 s10, 2, 0
	s_sub_u32 s11, s11, s16
	s_cmp_ge_u32 s11, 0x3600
	s_cselect_b32 s16, 0x3600, 0
	s_cselect_b32 s17, 1, 0
	s_sub_u32 s11, s11, s16
	s_add_u32 s10, s10, s17
	s_cmp_lt_u32 s11, 0x2400
	s_cbranch_scc1 .Ltr_in2
	s_cmp_lt_u32 s11, 0x3400
	s_cbranch_scc1 .Ltr_out2
	s_sub_u32 s11, s11, 0x3400
	s_lshr_b32 s16, s11, 5
	s_and_b32 s17, s11, 31
	s_movk_i32 s14, 0x2000
	s_movk_i32 s15, 0x800
	s_mov_b32 s35, 0x10000
	s_lshl_b32 s31, s10, 23
	s_lshl_b32 s11, s16, 19
	s_add_u32 s31, s31, s11
	s_lshl_b32 s11, s17, 8
	s_add_u32 s31, s31, s11
	s_add_u32 s31, s6, s31
	s_addc_u32 s11, s7, 0
	s_bfe_u32 s14, s17, 0x30001
	s_lshl_b32 s14, s14, 8
	s_lshr_b32 s15, s17, 4
	s_lshl_b32 s15, s15, 7
	s_add_u32 s14, s14, s15
	s_and_b32 s15, s17, 1
	s_lshl_b32 s15, s15, 6
	s_add_u32 s14, s14, s15
	s_lshl_b32 s14, s14, 11
	s_lshl_b32 s15, s16, 7
	s_add_u32 s14, s14, s15
	s_lshl_b32 s15, s10, 22
	s_add_u32 s14, s14, s15
	s_add_u32 s17, s14, 0xae00000
	s_mov_b32 s16, s31
	s_mov_b32 s31, s17
	s_mov_b32 s17, s11
	s_movk_i32 s14, 0x2000
	s_movk_i32 s15, 0x800
	s_branch .Ltr_dec2
.Ltr_in2:
	s_mul_hi_u32 s16, s11, 0x38e38e39
	s_lshr_b32 s16, s16, 5
	s_mul_i32 s17, s16, 0x90
	s_sub_u32 s17, s11, s17
	s_mov_b32 s35, 0x40000
	s_mul_i32 s31, s10, 0x9000000
	s_mul_i32 s11, s16, 0x240000
	s_add_u32 s31, s31, s11
	s_lshl_b32 s11, s17, 8
	s_add_u32 s31, s31, s11
	s_add_u32 s14, s2, s31
	s_addc_u32 s15, s3, 0
	s_mul_i32 s31, s10, 0x4800000
	s_lshl_b32 s11, s17, 19
	s_add_u32 s31, s31, s11
	s_lshl_b32 s11, s16, 7
	s_add_u32 s31, s31, s11
	s_add_u32 s31, s31, 0x14600000
	s_mov_b32 s16, s14
	s_mov_b32 s17, s15
	s_mov_b32 s14, 0x9000
	s_movk_i32 s15, 0x2000
	s_branch .Ltr_dec2
.Ltr_out2:
	s_sub_u32 s11, s11, 0x2400
	s_lshr_b32 s16, s11, 6
	s_and_b32 s17, s11, 63
	s_mov_b32 s35, 0x40000
	s_lshl_b32 s31, s10, 26
	s_lshl_b32 s11, s16, 20
	s_add_u32 s31, s31, s11
	s_lshl_b32 s11, s17, 8
	s_add_u32 s31, s31, s11
	s_add_u32 s14, s4, s31
	s_addc_u32 s15, s5, 0
	s_lshl_b32 s31, s10, 25
	s_lshl_b32 s11, s17, 19
	s_add_u32 s31, s31, s11
	s_lshl_b32 s11, s16, 7
	s_add_u32 s31, s31, s11
	s_add_u32 s31, s31, 0xc600000
	s_mov_b32 s16, s14
	s_mov_b32 s17, s15
	s_movk_i32 s14, 0x4000
	s_movk_i32 s15, 0x2000
.Ltr_dec2:
	s_add_u32 s40, s8, s31
	s_addc_u32 s41, s9, 0
	v_mad_u32_u24 v16, v3, s14, v2
	v_add_u32_e32 v17, s14, v16
	v_add_u32_e32 v18, s14, v17
	v_add_u32_e32 v19, s14, v18
	v_add_u32_e32 v20, s14, v19
	v_add_u32_e32 v21, s14, v20
	v_add_u32_e32 v22, s14, v21
	v_add_u32_e32 v23, s14, v22
	v_mad_u32_u24 v28, v4, s15, v5
	v_add_u32_e32 v29, s15, v28
	v_add_u32_e32 v30, s15, v29
	v_add_u32_e32 v31, s15, v30
	global_load_dwordx4 v[128:131], v16, s[16:17] nt
	global_load_dwordx4 v[132:135], v17, s[16:17] nt
	global_load_dwordx4 v[136:139], v18, s[16:17] nt
	global_load_dwordx4 v[140:143], v19, s[16:17] nt
	global_load_dwordx4 v[144:147], v20, s[16:17] nt
	global_load_dwordx4 v[148:151], v21, s[16:17] nt
	global_load_dwordx4 v[152:155], v22, s[16:17] nt
	global_load_dwordx4 v[156:159], v23, s[16:17] nt
	global_load_dwordx4 v[160:163], v16, s[16:17] offset:128 nt
	global_load_dwordx4 v[164:167], v17, s[16:17] offset:128 nt
	global_load_dwordx4 v[168:171], v18, s[16:17] offset:128 nt
	global_load_dwordx4 v[172:175], v19, s[16:17] offset:128 nt
	global_load_dwordx4 v[176:179], v20, s[16:17] offset:128 nt
	global_load_dwordx4 v[180:183], v21, s[16:17] offset:128 nt
	global_load_dwordx4 v[184:187], v22, s[16:17] offset:128 nt
	global_load_dwordx4 v[188:191], v23, s[16:17] offset:128 nt
	s_waitcnt vmcnt(16)
	v_cvt_pk_bf16_f32 v192, v64, v68
	v_cvt_pk_bf16_f32 v193, v72, v76
	v_cvt_pk_bf16_f32 v194, v80, v84
	v_cvt_pk_bf16_f32 v195, v88, v92
	v_cvt_pk_bf16_f32 v196, v65, v69
	v_cvt_pk_bf16_f32 v197, v73, v77
	v_cvt_pk_bf16_f32 v198, v81, v85
	v_cvt_pk_bf16_f32 v199, v89, v93
	v_cvt_pk_bf16_f32 v200, v66, v70
	v_cvt_pk_bf16_f32 v201, v74, v78
	v_cvt_pk_bf16_f32 v202, v82, v86
	v_cvt_pk_bf16_f32 v203, v90, v94
	v_cvt_pk_bf16_f32 v204, v67, v71
	v_cvt_pk_bf16_f32 v205, v75, v79
	v_cvt_pk_bf16_f32 v206, v83, v87
	v_cvt_pk_bf16_f32 v207, v91, v95
	global_store_dwordx4 v24, v[192:195], s[18:19]
	global_store_dwordx4 v25, v[196:199], s[18:19]
	global_store_dwordx4 v26, v[200:203], s[18:19]
	global_store_dwordx4 v27, v[204:207], s[18:19]
	v_cvt_pk_bf16_f32 v48, v96, v100
	v_cvt_pk_bf16_f32 v49, v104, v108
	v_cvt_pk_bf16_f32 v50, v112, v116
	v_cvt_pk_bf16_f32 v51, v120, v124
	v_cvt_pk_bf16_f32 v52, v97, v101
	v_cvt_pk_bf16_f32 v53, v105, v109
	v_cvt_pk_bf16_f32 v54, v113, v117
	v_cvt_pk_bf16_f32 v55, v121, v125
	v_cvt_pk_bf16_f32 v56, v98, v102
	v_cvt_pk_bf16_f32 v57, v106, v110
	v_cvt_pk_bf16_f32 v58, v114, v118
	v_cvt_pk_bf16_f32 v59, v122, v126
	v_cvt_pk_bf16_f32 v60, v99, v103
	v_cvt_pk_bf16_f32 v61, v107, v111
	v_cvt_pk_bf16_f32 v62, v115, v119
	v_cvt_pk_bf16_f32 v63, v123, v127
	s_add_u32 s10, s18, s34
	s_addc_u32 s11, s19, 0
	global_store_dwordx4 v24, v[48:51], s[10:11]
	global_store_dwordx4 v25, v[52:55], s[10:11]
	global_store_dwordx4 v26, v[56:59], s[10:11]
	global_store_dwordx4 v27, v[60:63], s[10:11]
	s_add_u32 s29, s29, s30
	s_cmp_gt_u32 s29, 0xd7ff
	s_cbranch_scc1 .Ltr_lastB
	s_mov_b32 s11, s29
	s_cmp_ge_u32 s11, 0x6c00
	s_cselect_b32 s16, 0x6c00, 0
	s_cselect_b32 s10, 2, 0
	s_sub_u32 s11, s11, s16
	s_cmp_ge_u32 s11, 0x3600
	s_cselect_b32 s16, 0x3600, 0
	s_cselect_b32 s17, 1, 0
	s_sub_u32 s11, s11, s16
	s_add_u32 s10, s10, s17
	s_cmp_lt_u32 s11, 0x2400
	s_cbranch_scc1 .Ltr_in3
	s_cmp_lt_u32 s11, 0x3400
	s_cbranch_scc1 .Ltr_out3
	s_sub_u32 s11, s11, 0x3400
	s_lshr_b32 s16, s11, 5
	s_and_b32 s17, s11, 31
	s_movk_i32 s14, 0x2000
	s_movk_i32 s15, 0x800
	s_mov_b32 s34, 0x10000
	s_lshl_b32 s31, s10, 23
	s_lshl_b32 s11, s16, 19
	s_add_u32 s31, s31, s11
	s_lshl_b32 s11, s17, 8
	s_add_u32 s31, s31, s11
	s_add_u32 s31, s6, s31
	s_addc_u32 s11, s7, 0
	s_bfe_u32 s14, s17, 0x30001
	s_lshl_b32 s14, s14, 8
	s_lshr_b32 s15, s17, 4
	s_lshl_b32 s15, s15, 7
	s_add_u32 s14, s14, s15
	s_and_b32 s15, s17, 1
	s_lshl_b32 s15, s15, 6
	s_add_u32 s14, s14, s15
	s_lshl_b32 s14, s14, 11
	s_lshl_b32 s15, s16, 7
	s_add_u32 s14, s14, s15
	s_lshl_b32 s15, s10, 22
	s_add_u32 s14, s14, s15
	s_add_u32 s17, s14, 0xae00000
	s_mov_b32 s16, s31
	s_mov_b32 s31, s17
	s_mov_b32 s17, s11
	s_movk_i32 s14, 0x2000
	s_movk_i32 s15, 0x800
	s_branch .Ltr_dec3

.Ltr_dec3:
	s_add_u32 s18, s8, s31
	s_addc_u32 s19, s9, 0
	v_mad_u32_u24 v16, v3, s14, v2
	v_add_u32_e32 v17, s14, v16
	v_add_u32_e32 v18, s14, v17
	v_add_u32_e32 v19, s14, v18
	v_add_u32_e32 v20, s14, v19
	v_add_u32_e32 v21, s14, v20
	v_add_u32_e32 v22, s14, v21
	v_add_u32_e32 v23, s14, v22
	v_mad_u32_u24 v24, v4, s15, v5
	v_add_u32_e32 v25, s15, v24
	v_add_u32_e32 v26, s15, v25
	v_add_u32_e32 v27, s15, v26
	global_load_dwordx4 v[64:67], v16, s[16:17] nt
	global_load_dwordx4 v[68:71], v17, s[16:17] nt
	global_load_dwordx4 v[72:75], v18, s[16:17] nt
	global_load_dwordx4 v[76:79], v19, s[16:17] nt
	global_load_dwordx4 v[80:83], v20, s[16:17] nt
	global_load_dwordx4 v[84:87], v21, s[16:17] nt
	global_load_dwordx4 v[88:91], v22, s[16:17] nt
	global_load_dwordx4 v[92:95], v23, s[16:17] nt
	global_load_dwordx4 v[96:99], v16, s[16:17] offset:128 nt
	global_load_dwordx4 v[100:103], v17, s[16:17] offset:128 nt
	global_load_dwordx4 v[104:107], v18, s[16:17] offset:128 nt
	global_load_dwordx4 v[108:111], v19, s[16:17] offset:128 nt
	global_load_dwordx4 v[112:115], v20, s[16:17] offset:128 nt
	global_load_dwordx4 v[116:119], v21, s[16:17] offset:128 nt
	global_load_dwordx4 v[120:123], v22, s[16:17] offset:128 nt
	global_load_dwordx4 v[124:127], v23, s[16:17] offset:128 nt
	s_waitcnt vmcnt(16)
	v_cvt_pk_bf16_f32 v192, v128, v132
	v_cvt_pk_bf16_f32 v193, v136, v140
	v_cvt_pk_bf16_f32 v194, v144, v148
	v_cvt_pk_bf16_f32 v195, v152, v156
	v_cvt_pk_bf16_f32 v196, v129, v133
	v_cvt_pk_bf16_f32 v197, v137, v141
	v_cvt_pk_bf16_f32 v198, v145, v149
	v_cvt_pk_bf16_f32 v199, v153, v157
	v_cvt_pk_bf16_f32 v200, v130, v134
	v_cvt_pk_bf16_f32 v201, v138, v142
	v_cvt_pk_bf16_f32 v202, v146, v150
	v_cvt_pk_bf16_f32 v203, v154, v158
	v_cvt_pk_bf16_f32 v204, v131, v135
	v_cvt_pk_bf16_f32 v205, v139, v143
	v_cvt_pk_bf16_f32 v206, v147, v151
	v_cvt_pk_bf16_f32 v207, v155, v159
	global_store_dwordx4 v28, v[192:195], s[40:41]
	global_store_dwordx4 v29, v[196:199], s[40:41]
	global_store_dwordx4 v30, v[200:203], s[40:41]
	global_store_dwordx4 v31, v[204:207], s[40:41]
	v_cvt_pk_bf16_f32 v48, v160, v164
	v_cvt_pk_bf16_f32 v49, v168, v172
	v_cvt_pk_bf16_f32 v50, v176, v180
	v_cvt_pk_bf16_f32 v51, v184, v188
	v_cvt_pk_bf16_f32 v52, v161, v165
	v_cvt_pk_bf16_f32 v53, v169, v173
	v_cvt_pk_bf16_f32 v54, v177, v181
	v_cvt_pk_bf16_f32 v55, v185, v189
	v_cvt_pk_bf16_f32 v56, v162, v166
	v_cvt_pk_bf16_f32 v57, v170, v174
	v_cvt_pk_bf16_f32 v58, v178, v182
	v_cvt_pk_bf16_f32 v59, v186, v190
	v_cvt_pk_bf16_f32 v60, v163, v167
	v_cvt_pk_bf16_f32 v61, v171, v175
	v_cvt_pk_bf16_f32 v62, v179, v183
	v_cvt_pk_bf16_f32 v63, v187, v191
	s_add_u32 s10, s40, s35
	s_addc_u32 s11, s41, 0
	global_store_dwordx4 v28, v[48:51], s[10:11]
	global_store_dwordx4 v29, v[52:55], s[10:11]
	global_store_dwordx4 v30, v[56:59], s[10:11]
	global_store_dwordx4 v31, v[60:63], s[10:11]
	s_branch .Ltr_loop
.Ltr_lastA:
	s_waitcnt vmcnt(0)
	v_cvt_pk_bf16_f32 v192, v64, v68
	v_cvt_pk_bf16_f32 v193, v72, v76
	v_cvt_pk_bf16_f32 v194, v80, v84
	v_cvt_pk_bf16_f32 v195, v88, v92
	v_cvt_pk_bf16_f32 v196, v65, v69
	v_cvt_pk_bf16_f32 v197, v73, v77
	v_cvt_pk_bf16_f32 v198, v81, v85
	v_cvt_pk_bf16_f32 v199, v89, v93
	v_cvt_pk_bf16_f32 v200, v66, v70
	v_cvt_pk_bf16_f32 v201, v74, v78
	v_cvt_pk_bf16_f32 v202, v82, v86
	v_cvt_pk_bf16_f32 v203, v90, v94
	v_cvt_pk_bf16_f32 v204, v67, v71
	v_cvt_pk_bf16_f32 v205, v75, v79
	v_cvt_pk_bf16_f32 v206, v83, v87
	v_cvt_pk_bf16_f32 v207, v91, v95
	global_store_dwordx4 v24, v[192:195], s[18:19]
	global_store_dwordx4 v25, v[196:199], s[18:19]
	global_store_dwordx4 v26, v[200:203], s[18:19]
	global_store_dwordx4 v27, v[204:207], s[18:19]
	v_cvt_pk_bf16_f32 v48, v96, v100
	v_cvt_pk_bf16_f32 v49, v104, v108
	v_cvt_pk_bf16_f32 v50, v112, v116
	v_cvt_pk_bf16_f32 v51, v120, v124
	v_cvt_pk_bf16_f32 v52, v97, v101
	v_cvt_pk_bf16_f32 v53, v105, v109
	v_cvt_pk_bf16_f32 v54, v113, v117
	v_cvt_pk_bf16_f32 v55, v121, v125
	v_cvt_pk_bf16_f32 v56, v98, v102
	v_cvt_pk_bf16_f32 v57, v106, v110
	v_cvt_pk_bf16_f32 v58, v114, v118
	v_cvt_pk_bf16_f32 v59, v122, v126
	v_cvt_pk_bf16_f32 v60, v99, v103
	v_cvt_pk_bf16_f32 v61, v107, v111
	v_cvt_pk_bf16_f32 v62, v115, v119
	v_cvt_pk_bf16_f32 v63, v123, v127
	s_add_u32 s10, s18, s34
	s_addc_u32 s11, s19, 0
	global_store_dwordx4 v24, v[48:51], s[10:11]
	global_store_dwordx4 v25, v[52:55], s[10:11]
	global_store_dwordx4 v26, v[56:59], s[10:11]
	global_store_dwordx4 v27, v[60:63], s[10:11]
	s_branch .LBB0_58
.Ltr_lastB:
	s_waitcnt vmcnt(0)
	v_cvt_pk_bf16_f32 v192, v128, v132
	v_cvt_pk_bf16_f32 v193, v136, v140
	v_cvt_pk_bf16_f32 v194, v144, v148
	v_cvt_pk_bf16_f32 v195, v152, v156
	v_cvt_pk_bf16_f32 v196, v129, v133
	v_cvt_pk_bf16_f32 v197, v137, v141
	v_cvt_pk_bf16_f32 v198, v145, v149
	v_cvt_pk_bf16_f32 v199, v153, v157
	v_cvt_pk_bf16_f32 v200, v130, v134
	v_cvt_pk_bf16_f32 v201, v138, v142
	v_cvt_pk_bf16_f32 v202, v146, v150
	v_cvt_pk_bf16_f32 v203, v154, v158
	v_cvt_pk_bf16_f32 v204, v131, v135
	v_cvt_pk_bf16_f32 v205, v139, v143
	v_cvt_pk_bf16_f32 v206, v147, v151
	v_cvt_pk_bf16_f32 v207, v155, v159
	global_store_dwordx4 v28, v[192:195], s[40:41]
	global_store_dwordx4 v29, v[196:199], s[40:41]
	global_store_dwordx4 v30, v[200:203], s[40:41]
	global_store_dwordx4 v31, v[204:207], s[40:41]
	v_cvt_pk_bf16_f32 v48, v160, v164
	v_cvt_pk_bf16_f32 v49, v168, v172
	v_cvt_pk_bf16_f32 v50, v176, v180
	v_cvt_pk_bf16_f32 v51, v184, v188
	v_cvt_pk_bf16_f32 v52, v161, v165
	v_cvt_pk_bf16_f32 v53, v169, v173
	v_cvt_pk_bf16_f32 v54, v177, v181
	v_cvt_pk_bf16_f32 v55, v185, v189
	v_cvt_pk_bf16_f32 v56, v162, v166
	v_cvt_pk_bf16_f32 v57, v170, v174
	v_cvt_pk_bf16_f32 v58, v178, v182
	v_cvt_pk_bf16_f32 v59, v186, v190
	v_cvt_pk_bf16_f32 v60, v163, v167
	v_cvt_pk_bf16_f32 v61, v171, v175
	v_cvt_pk_bf16_f32 v62, v179, v183
	v_cvt_pk_bf16_f32 v63, v187, v191
	s_add_u32 s10, s40, s35
	s_addc_u32 s11, s41, 0
	global_store_dwordx4 v28, v[48:51], s[10:11]
	global_store_dwordx4 v29, v[52:55], s[10:11]
	global_store_dwordx4 v30, v[56:59], s[10:11]
	global_store_dwordx4 v31, v[60:63], s[10:11]

.LBB0_61:
	s_and_saveexec_b64 s[18:19], s[2:3]
	s_cbranch_execz .LBB0_68
	s_load_dwordx2 s[54:55], s[24:25], 0x48
	s_load_dwordx2 s[56:57], s[24:25], 0x40
	v_lshlrev_b32_e32 v100, 2, v44
	v_add_u32_e32 v101, 0x1000, v100
	v_add_u32_e32 v102, 0x2000, v100
	v_add_u32_e32 v103, 0x3000, v100
	s_waitcnt lgkmcnt(0)
	s_add_u32 s10, s56, 0x4000
	s_addc_u32 s11, s57, 0
	global_load_dword v108, v100, s[54:55]
	global_load_dword v109, v100, s[54:55] offset:2048
	global_load_dword v110, v101, s[54:55]
	global_load_dword v111, v101, s[54:55] offset:2048
	global_load_dword v112, v102, s[54:55]
	global_load_dword v113, v102, s[54:55] offset:2048
	global_load_dword v114, v103, s[54:55]
	global_load_dword v115, v103, s[54:55] offset:2048
	global_load_dword v116, v100, s[56:57]
	global_load_dword v117, v100, s[56:57] offset:2048
	global_load_dword v118, v101, s[56:57]
	global_load_dword v119, v101, s[56:57] offset:2048
	global_load_dword v120, v102, s[56:57]
	global_load_dword v121, v102, s[56:57] offset:2048
	global_load_dword v122, v103, s[56:57]
	global_load_dword v123, v103, s[56:57] offset:2048
	global_load_dword v124, v100, s[10:11]
	global_load_dword v125, v100, s[10:11] offset:2048
	global_load_dword v126, v101, s[10:11]
	global_load_dword v127, v101, s[10:11] offset:2048
	global_load_dword v128, v102, s[10:11]
	global_load_dword v129, v102, s[10:11] offset:2048
	global_load_dword v130, v103, s[10:11]
	global_load_dword v131, v103, s[10:11] offset:2048
	s_waitcnt vmcnt(0)
	ds_write_b32 v22, v108
	ds_write_b32 v22, v109 offset:2048
	ds_write_b32 v22, v110 offset:4096
	ds_write_b32 v22, v111 offset:6144
	ds_write_b32 v22, v112 offset:8192
	ds_write_b32 v22, v113 offset:10240
	ds_write_b32 v22, v114 offset:12288
	ds_write_b32 v22, v115 offset:14336
	ds_write_b32 v22, v116 offset:16384
	ds_write_b32 v22, v117 offset:18432
	ds_write_b32 v22, v118 offset:20480
	ds_write_b32 v22, v119 offset:22528
	ds_write_b32 v22, v120 offset:24576
	ds_write_b32 v22, v121 offset:26624
	ds_write_b32 v22, v122 offset:28672
	ds_write_b32 v22, v123 offset:30720
	ds_write_b32 v22, v124 offset:32768
	ds_write_b32 v22, v125 offset:34816
	ds_write_b32 v22, v126 offset:36864
	ds_write_b32 v22, v127 offset:38912
	ds_write_b32 v22, v128 offset:40960
	ds_write_b32 v22, v129 offset:43008
	ds_write_b32 v22, v130 offset:45056
	ds_write_b32 v22, v131 offset:47104
	v_mov_b32_e32 v2, v22
	s_mov_b32 s30, 0
.Lsilu_loop:
	ds_read_b32 v0, v2
	s_waitcnt lgkmcnt(0)
	v_mul_f32_e32 v1, 0xbfb8aa3b, v0
	v_rndne_f32_e32 v4, v1
	v_fma_f32 v5, v0, s41, -v1
	v_sub_f32_e32 v1, v1, v4
	v_fmac_f32_e32 v5, 0xb2a5705f, v0
	v_add_f32_e32 v1, v1, v5
	v_cvt_i32_f32_e32 v4, v4
	v_exp_f32_e32 v1, v1
	v_cmp_nlt_f32_e64 s[10:11], s42, v0
	s_nop 0
	v_ldexp_f32 v1, v1, v4
	v_cndmask_b32_e64 v1, 0, v1, s[10:11]
	v_cmp_ngt_f32_e64 s[10:11], s43, v0
	s_nop 1
	v_cndmask_b32_e64 v1, v23, v1, s[10:11]
	v_add_f32_e32 v1, 1.0, v1
	v_div_scale_f32 v3, s[10:11], v1, v1, v0
	v_rcp_f32_e32 v4, v3
	v_div_scale_f32 v6, vcc, v0, v1, v0
	v_fma_f32 v7, -v3, v4, 1.0
	v_fmac_f32_e32 v4, v7, v4
	v_mul_f32_e32 v7, v6, v4
	v_fma_f32 v8, -v3, v7, v6
	v_fmac_f32_e32 v7, v8, v4
	v_fma_f32 v3, -v3, v7, v6
	v_div_fmas_f32 v3, v3, v4, v7
	v_div_fixup_f32 v0, v3, v1, v0
	ds_write_b32 v2, v0
	v_add_u32_e32 v2, 0x800, v2
	s_add_u32 s30, s30, 1
	s_cmp_lt_u32 s30, 24
	s_cbranch_scc1 .Lsilu_loop

.LBB0_69:
	v_readfirstlane_b32 s54, v18
	v_readfirstlane_b32 s55, v19
	s_nop 1
	v_subrev_u32_e32 v100, s54, v18
	v_add_u32_e32 v101, 0xc000, v100
	v_add_u32_e32 v102, 0x18000, v100
	v_add_u32_e32 v103, 0x24000, v100
	v_add_u32_e32 v104, 0x30000, v100
	v_add_u32_e32 v105, 0x3c000, v100
	v_add_u32_e32 v106, 0x48000, v100
	v_add_u32_e32 v107, 0x54000, v100
	s_mov_b32 s56, 0
	global_load_dwordx4 v[24:27], v100, s[54:55] nt
	global_load_dwordx4 v[28:31], v101, s[54:55] nt
	global_load_dwordx4 v[32:35], v102, s[54:55] nt
	global_load_dwordx4 v[36:39], v103, s[54:55] nt
	global_load_dwordx4 v[40:43], v104, s[54:55] nt
	global_load_dwordx4 v[48:51], v105, s[54:55] nt
	global_load_dwordx4 v[52:55], v106, s[54:55] nt
	global_load_dwordx4 v[56:59], v107, s[54:55] nt
	s_add_u32 s54, s54, 0x60000
	s_addc_u32 s55, s55, 0
.Lgv_loop:
	global_load_dwordx4 v[108:111], v100, s[54:55] nt
	global_load_dwordx4 v[112:115], v101, s[54:55] nt
	global_load_dwordx4 v[116:119], v102, s[54:55] nt
	global_load_dwordx4 v[120:123], v103, s[54:55] nt
	global_load_dwordx4 v[124:127], v104, s[54:55] nt
	global_load_dwordx4 v[128:131], v105, s[54:55] nt
	global_load_dwordx4 v[132:135], v106, s[54:55] nt
	global_load_dwordx4 v[136:139], v107, s[54:55] nt
	s_add_u32 s54, s54, 0x60000
	s_addc_u32 s55, s55, 0
	v_mov_b32_e32 v14, s18
	s_add_i32 s18, s18, 32
	ds_read_b128 v[60:63], v14
	ds_read_b128 v[64:67], v14 offset:16
	ds_read_b128 v[68:71], v14 offset:16384
	ds_read_b128 v[72:75], v14 offset:16400
	ds_read_b128 v[76:79], v14 offset:32768
	ds_read_b128 v[80:83], v14 offset:32784
	s_waitcnt lgkmcnt(5)
	v_mov_b32_e32 v14, v63
	s_waitcnt lgkmcnt(3)
	v_mov_b32_e32 v84, v71
	v_mov_b32_e32 v88, v67
	s_waitcnt lgkmcnt(1)
	v_mov_b32_e32 v86, v79
	v_mov_b32_e32 v90, v75
	s_waitcnt lgkmcnt(0)
	v_mov_b32_e32 v92, v83
	s_waitcnt vmcnt(15)
	v_pk_fma_f32 v[2:3], v[26:27], v[60:61], v[2:3] op_sel_hi:[1,0,1]
	v_pk_fma_f32 v[0:1], v[24:25], v[60:61], v[0:1] op_sel_hi:[1,0,1]
	v_pk_fma_f32 v[6:7], v[26:27], v[68:69], v[6:7] op_sel_hi:[1,0,1]
	v_pk_fma_f32 v[4:5], v[24:25], v[68:69], v[4:5] op_sel_hi:[1,0,1]
	v_pk_fma_f32 v[10:11], v[26:27], v[76:77], v[10:11] op_sel_hi:[1,0,1]
	v_pk_fma_f32 v[8:9], v[24:25], v[76:77], v[8:9] op_sel_hi:[1,0,1]
	s_waitcnt vmcnt(14)
	v_pk_fma_f32 v[0:1], v[28:29], v[60:61], v[0:1] op_sel:[0,1,0]
	v_pk_fma_f32 v[2:3], v[30:31], v[60:61], v[2:3] op_sel:[0,1,0]
	v_pk_fma_f32 v[4:5], v[28:29], v[68:69], v[4:5] op_sel:[0,1,0]
	v_pk_fma_f32 v[6:7], v[30:31], v[68:69], v[6:7] op_sel:[0,1,0]
	v_pk_fma_f32 v[8:9], v[28:29], v[76:77], v[8:9] op_sel:[0,1,0]
	v_pk_fma_f32 v[10:11], v[30:31], v[76:77], v[10:11] op_sel:[0,1,0]
	s_waitcnt vmcnt(13)
	v_pk_fma_f32 v[2:3], v[34:35], v[62:63], v[2:3] op_sel_hi:[1,0,1]
	v_pk_fma_f32 v[0:1], v[32:33], v[62:63], v[0:1] op_sel_hi:[1,0,1]
	v_pk_fma_f32 v[6:7], v[34:35], v[70:71], v[6:7] op_sel_hi:[1,0,1]
	v_pk_fma_f32 v[4:5], v[32:33], v[70:71], v[4:5] op_sel_hi:[1,0,1]
	v_pk_fma_f32 v[10:11], v[34:35], v[78:79], v[10:11] op_sel_hi:[1,0,1]
	v_pk_fma_f32 v[8:9], v[32:33], v[78:79], v[8:9] op_sel_hi:[1,0,1]
	s_waitcnt vmcnt(12)
	v_pk_fma_f32 v[2:3], v[38:39], v[14:15], v[2:3] op_sel_hi:[1,0,1]
	v_pk_fma_f32 v[0:1], v[36:37], v[14:15], v[0:1] op_sel_hi:[1,0,1]
	v_pk_fma_f32 v[6:7], v[38:39], v[84:85], v[6:7] op_sel_hi:[1,0,1]
	v_pk_fma_f32 v[4:5], v[36:37], v[84:85], v[4:5] op_sel_hi:[1,0,1]
	v_pk_fma_f32 v[10:11], v[38:39], v[86:87], v[10:11] op_sel_hi:[1,0,1]
	v_pk_fma_f32 v[8:9], v[36:37], v[86:87], v[8:9] op_sel_hi:[1,0,1]
	s_waitcnt vmcnt(11)
	v_pk_fma_f32 v[2:3], v[42:43], v[64:65], v[2:3] op_sel_hi:[1,0,1]
	v_pk_fma_f32 v[0:1], v[40:41], v[64:65], v[0:1] op_sel_hi:[1,0,1]
	v_pk_fma_f32 v[6:7], v[42:43], v[72:73], v[6:7] op_sel_hi:[1,0,1]
	v_pk_fma_f32 v[4:5], v[40:41], v[72:73], v[4:5] op_sel_hi:[1,0,1]
	v_pk_fma_f32 v[10:11], v[42:43], v[80:81], v[10:11] op_sel_hi:[1,0,1]
	v_pk_fma_f32 v[8:9], v[40:41], v[80:81], v[8:9] op_sel_hi:[1,0,1]
	s_waitcnt vmcnt(10)
	v_pk_fma_f32 v[2:3], v[50:51], v[64:65], v[2:3] op_sel:[0,1,0]
	v_pk_fma_f32 v[0:1], v[48:49], v[64:65], v[0:1] op_sel:[0,1,0]
	v_pk_fma_f32 v[6:7], v[50:51], v[72:73], v[6:7] op_sel:[0,1,0]
	v_pk_fma_f32 v[4:5], v[48:49], v[72:73], v[4:5] op_sel:[0,1,0]
	v_pk_fma_f32 v[10:11], v[50:51], v[80:81], v[10:11] op_sel:[0,1,0]
	v_pk_fma_f32 v[8:9], v[48:49], v[80:81], v[8:9] op_sel:[0,1,0]
	s_waitcnt vmcnt(9)
	v_pk_fma_f32 v[2:3], v[54:55], v[66:67], v[2:3] op_sel_hi:[1,0,1]
	v_pk_fma_f32 v[0:1], v[52:53], v[66:67], v[0:1] op_sel_hi:[1,0,1]
	v_pk_fma_f32 v[6:7], v[54:55], v[74:75], v[6:7] op_sel_hi:[1,0,1]
	v_pk_fma_f32 v[4:5], v[52:53], v[74:75], v[4:5] op_sel_hi:[1,0,1]
	v_pk_fma_f32 v[10:11], v[54:55], v[82:83], v[10:11] op_sel_hi:[1,0,1]
	v_pk_fma_f32 v[8:9], v[52:53], v[82:83], v[8:9] op_sel_hi:[1,0,1]
	s_waitcnt vmcnt(8)
	v_pk_fma_f32 v[2:3], v[58:59], v[88:89], v[2:3] op_sel_hi:[1,0,1]
	v_pk_fma_f32 v[0:1], v[56:57], v[88:89], v[0:1] op_sel_hi:[1,0,1]
	v_pk_fma_f32 v[6:7], v[58:59], v[90:91], v[6:7] op_sel_hi:[1,0,1]
	v_pk_fma_f32 v[4:5], v[56:57], v[90:91], v[4:5] op_sel_hi:[1,0,1]
	v_pk_fma_f32 v[10:11], v[58:59], v[92:93], v[10:11] op_sel_hi:[1,0,1]
	v_pk_fma_f32 v[8:9], v[56:57], v[92:93], v[8:9] op_sel_hi:[1,0,1]
	s_add_u32 s56, s56, 1
	s_cmp_eq_u32 s56, 32
	s_cbranch_scc1 .Lgv_tail
	global_load_dwordx4 v[24:27], v100, s[54:55] nt
	global_load_dwordx4 v[28:31], v101, s[54:55] nt
	global_load_dwordx4 v[32:35], v102, s[54:55] nt
	global_load_dwordx4 v[36:39], v103, s[54:55] nt
	global_load_dwordx4 v[40:43], v104, s[54:55] nt
	global_load_dwordx4 v[48:51], v105, s[54:55] nt
	global_load_dwordx4 v[52:55], v106, s[54:55] nt
	global_load_dwordx4 v[56:59], v107, s[54:55] nt
	s_add_u32 s54, s54, 0x60000
	s_addc_u32 s55, s55, 0
	v_mov_b32_e32 v14, s18
	s_add_i32 s18, s18, 32
	ds_read_b128 v[60:63], v14
	ds_read_b128 v[64:67], v14 offset:16
	ds_read_b128 v[68:71], v14 offset:16384
	ds_read_b128 v[72:75], v14 offset:16400
	ds_read_b128 v[76:79], v14 offset:32768
	ds_read_b128 v[80:83], v14 offset:32784
	s_waitcnt lgkmcnt(5)
	v_mov_b32_e32 v14, v63
	s_waitcnt lgkmcnt(3)
	v_mov_b32_e32 v84, v71
	v_mov_b32_e32 v88, v67
	s_waitcnt lgkmcnt(1)
	v_mov_b32_e32 v86, v79
	v_mov_b32_e32 v90, v75
	s_waitcnt lgkmcnt(0)
	v_mov_b32_e32 v92, v83
	s_waitcnt vmcnt(15)
	v_pk_fma_f32 v[2:3], v[110:111], v[60:61], v[2:3] op_sel_hi:[1,0,1]
	v_pk_fma_f32 v[0:1], v[108:109], v[60:61], v[0:1] op_sel_hi:[1,0,1]
	v_pk_fma_f32 v[6:7], v[110:111], v[68:69], v[6:7] op_sel_hi:[1,0,1]
	v_pk_fma_f32 v[4:5], v[108:109], v[68:69], v[4:5] op_sel_hi:[1,0,1]
	v_pk_fma_f32 v[10:11], v[110:111], v[76:77], v[10:11] op_sel_hi:[1,0,1]
	v_pk_fma_f32 v[8:9], v[108:109], v[76:77], v[8:9] op_sel_hi:[1,0,1]
	s_waitcnt vmcnt(14)
	v_pk_fma_f32 v[0:1], v[112:113], v[60:61], v[0:1] op_sel:[0,1,0]
	v_pk_fma_f32 v[2:3], v[114:115], v[60:61], v[2:3] op_sel:[0,1,0]
	v_pk_fma_f32 v[4:5], v[112:113], v[68:69], v[4:5] op_sel:[0,1,0]
	v_pk_fma_f32 v[6:7], v[114:115], v[68:69], v[6:7] op_sel:[0,1,0]
	v_pk_fma_f32 v[8:9], v[112:113], v[76:77], v[8:9] op_sel:[0,1,0]
	v_pk_fma_f32 v[10:11], v[114:115], v[76:77], v[10:11] op_sel:[0,1,0]
	s_waitcnt vmcnt(13)
	v_pk_fma_f32 v[2:3], v[118:119], v[62:63], v[2:3] op_sel_hi:[1,0,1]
	v_pk_fma_f32 v[0:1], v[116:117], v[62:63], v[0:1] op_sel_hi:[1,0,1]
	v_pk_fma_f32 v[6:7], v[118:119], v[70:71], v[6:7] op_sel_hi:[1,0,1]
	v_pk_fma_f32 v[4:5], v[116:117], v[70:71], v[4:5] op_sel_hi:[1,0,1]
	v_pk_fma_f32 v[10:11], v[118:119], v[78:79], v[10:11] op_sel_hi:[1,0,1]
	v_pk_fma_f32 v[8:9], v[116:117], v[78:79], v[8:9] op_sel_hi:[1,0,1]
	s_waitcnt vmcnt(12)
	v_pk_fma_f32 v[2:3], v[122:123], v[14:15], v[2:3] op_sel_hi:[1,0,1]
	v_pk_fma_f32 v[0:1], v[120:121], v[14:15], v[0:1] op_sel_hi:[1,0,1]
	v_pk_fma_f32 v[6:7], v[122:123], v[84:85], v[6:7] op_sel_hi:[1,0,1]
	v_pk_fma_f32 v[4:5], v[120:121], v[84:85], v[4:5] op_sel_hi:[1,0,1]
	v_pk_fma_f32 v[10:11], v[122:123], v[86:87], v[10:11] op_sel_hi:[1,0,1]
	v_pk_fma_f32 v[8:9], v[120:121], v[86:87], v[8:9] op_sel_hi:[1,0,1]
	s_waitcnt vmcnt(11)
	v_pk_fma_f32 v[2:3], v[126:127], v[64:65], v[2:3] op_sel_hi:[1,0,1]
	v_pk_fma_f32 v[0:1], v[124:125], v[64:65], v[0:1] op_sel_hi:[1,0,1]
	v_pk_fma_f32 v[6:7], v[126:127], v[72:73], v[6:7] op_sel_hi:[1,0,1]
	v_pk_fma_f32 v[4:5], v[124:125], v[72:73], v[4:5] op_sel_hi:[1,0,1]
	v_pk_fma_f32 v[10:11], v[126:127], v[80:81], v[10:11] op_sel_hi:[1,0,1]
	v_pk_fma_f32 v[8:9], v[124:125], v[80:81], v[8:9] op_sel_hi:[1,0,1]
	s_waitcnt vmcnt(10)
	v_pk_fma_f32 v[2:3], v[130:131], v[64:65], v[2:3] op_sel:[0,1,0]
	v_pk_fma_f32 v[0:1], v[128:129], v[64:65], v[0:1] op_sel:[0,1,0]
	v_pk_fma_f32 v[6:7], v[130:131], v[72:73], v[6:7] op_sel:[0,1,0]
	v_pk_fma_f32 v[4:5], v[128:129], v[72:73], v[4:5] op_sel:[0,1,0]
	v_pk_fma_f32 v[10:11], v[130:131], v[80:81], v[10:11] op_sel:[0,1,0]
	v_pk_fma_f32 v[8:9], v[128:129], v[80:81], v[8:9] op_sel:[0,1,0]
	s_waitcnt vmcnt(9)
	v_pk_fma_f32 v[2:3], v[134:135], v[66:67], v[2:3] op_sel_hi:[1,0,1]
	v_pk_fma_f32 v[0:1], v[132:133], v[66:67], v[0:1] op_sel_hi:[1,0,1]
	v_pk_fma_f32 v[6:7], v[134:135], v[74:75], v[6:7] op_sel_hi:[1,0,1]
	v_pk_fma_f32 v[4:5], v[132:133], v[74:75], v[4:5] op_sel_hi:[1,0,1]
	v_pk_fma_f32 v[10:11], v[134:135], v[82:83], v[10:11] op_sel_hi:[1,0,1]
	v_pk_fma_f32 v[8:9], v[132:133], v[82:83], v[8:9] op_sel_hi:[1,0,1]
	s_waitcnt vmcnt(8)
	v_pk_fma_f32 v[2:3], v[138:139], v[88:89], v[2:3] op_sel_hi:[1,0,1]
	v_pk_fma_f32 v[0:1], v[136:137], v[88:89], v[0:1] op_sel_hi:[1,0,1]
	v_pk_fma_f32 v[6:7], v[138:139], v[90:91], v[6:7] op_sel_hi:[1,0,1]
	v_pk_fma_f32 v[4:5], v[136:137], v[90:91], v[4:5] op_sel_hi:[1,0,1]
	v_pk_fma_f32 v[10:11], v[138:139], v[92:93], v[10:11] op_sel_hi:[1,0,1]
	v_pk_fma_f32 v[8:9], v[136:137], v[92:93], v[8:9] op_sel_hi:[1,0,1]
	s_branch .Lgv_loop
.Lgv_tail:
	v_mov_b32_e32 v14, s18
	s_add_i32 s18, s18, 32
	ds_read_b128 v[60:63], v14
	ds_read_b128 v[64:67], v14 offset:16
	ds_read_b128 v[68:71], v14 offset:16384
	ds_read_b128 v[72:75], v14 offset:16400
	ds_read_b128 v[76:79], v14 offset:32768
	ds_read_b128 v[80:83], v14 offset:32784
	s_waitcnt lgkmcnt(5)
	v_mov_b32_e32 v14, v63
	s_waitcnt lgkmcnt(3)
	v_mov_b32_e32 v84, v71
	v_mov_b32_e32 v88, v67
	s_waitcnt lgkmcnt(1)
	v_mov_b32_e32 v86, v79
	v_mov_b32_e32 v90, v75
	s_waitcnt lgkmcnt(0)
	v_mov_b32_e32 v92, v83
	s_waitcnt vmcnt(7)
	v_pk_fma_f32 v[2:3], v[110:111], v[60:61], v[2:3] op_sel_hi:[1,0,1]
	v_pk_fma_f32 v[0:1], v[108:109], v[60:61], v[0:1] op_sel_hi:[1,0,1]
	v_pk_fma_f32 v[6:7], v[110:111], v[68:69], v[6:7] op_sel_hi:[1,0,1]
	v_pk_fma_f32 v[4:5], v[108:109], v[68:69], v[4:5] op_sel_hi:[1,0,1]
	v_pk_fma_f32 v[10:11], v[110:111], v[76:77], v[10:11] op_sel_hi:[1,0,1]
	v_pk_fma_f32 v[8:9], v[108:109], v[76:77], v[8:9] op_sel_hi:[1,0,1]
	s_waitcnt vmcnt(6)
	v_pk_fma_f32 v[0:1], v[112:113], v[60:61], v[0:1] op_sel:[0,1,0]
	v_pk_fma_f32 v[2:3], v[114:115], v[60:61], v[2:3] op_sel:[0,1,0]
	v_pk_fma_f32 v[4:5], v[112:113], v[68:69], v[4:5] op_sel:[0,1,0]
	v_pk_fma_f32 v[6:7], v[114:115], v[68:69], v[6:7] op_sel:[0,1,0]
	v_pk_fma_f32 v[8:9], v[112:113], v[76:77], v[8:9] op_sel:[0,1,0]
	v_pk_fma_f32 v[10:11], v[114:115], v[76:77], v[10:11] op_sel:[0,1,0]
	s_waitcnt vmcnt(5)
	v_pk_fma_f32 v[2:3], v[118:119], v[62:63], v[2:3] op_sel_hi:[1,0,1]
	v_pk_fma_f32 v[0:1], v[116:117], v[62:63], v[0:1] op_sel_hi:[1,0,1]
	v_pk_fma_f32 v[6:7], v[118:119], v[70:71], v[6:7] op_sel_hi:[1,0,1]
	v_pk_fma_f32 v[4:5], v[116:117], v[70:71], v[4:5] op_sel_hi:[1,0,1]
	v_pk_fma_f32 v[10:11], v[118:119], v[78:79], v[10:11] op_sel_hi:[1,0,1]
	v_pk_fma_f32 v[8:9], v[116:117], v[78:79], v[8:9] op_sel_hi:[1,0,1]
	s_waitcnt vmcnt(4)
	v_pk_fma_f32 v[2:3], v[122:123], v[14:15], v[2:3] op_sel_hi:[1,0,1]
	v_pk_fma_f32 v[0:1], v[120:121], v[14:15], v[0:1] op_sel_hi:[1,0,1]
	v_pk_fma_f32 v[6:7], v[122:123], v[84:85], v[6:7] op_sel_hi:[1,0,1]
	v_pk_fma_f32 v[4:5], v[120:121], v[84:85], v[4:5] op_sel_hi:[1,0,1]
	v_pk_fma_f32 v[10:11], v[122:123], v[86:87], v[10:11] op_sel_hi:[1,0,1]
	v_pk_fma_f32 v[8:9], v[120:121], v[86:87], v[8:9] op_sel_hi:[1,0,1]
	s_waitcnt vmcnt(3)
	v_pk_fma_f32 v[2:3], v[126:127], v[64:65], v[2:3] op_sel_hi:[1,0,1]
	v_pk_fma_f32 v[0:1], v[124:125], v[64:65], v[0:1] op_sel_hi:[1,0,1]
	v_pk_fma_f32 v[6:7], v[126:127], v[72:73], v[6:7] op_sel_hi:[1,0,1]
	v_pk_fma_f32 v[4:5], v[124:125], v[72:73], v[4:5] op_sel_hi:[1,0,1]
	v_pk_fma_f32 v[10:11], v[126:127], v[80:81], v[10:11] op_sel_hi:[1,0,1]
	v_pk_fma_f32 v[8:9], v[124:125], v[80:81], v[8:9] op_sel_hi:[1,0,1]
	s_waitcnt vmcnt(2)
	v_pk_fma_f32 v[2:3], v[130:131], v[64:65], v[2:3] op_sel:[0,1,0]
	v_pk_fma_f32 v[0:1], v[128:129], v[64:65], v[0:1] op_sel:[0,1,0]
	v_pk_fma_f32 v[6:7], v[130:131], v[72:73], v[6:7] op_sel:[0,1,0]
	v_pk_fma_f32 v[4:5], v[128:129], v[72:73], v[4:5] op_sel:[0,1,0]
	v_pk_fma_f32 v[10:11], v[130:131], v[80:81], v[10:11] op_sel:[0,1,0]
	v_pk_fma_f32 v[8:9], v[128:129], v[80:81], v[8:9] op_sel:[0,1,0]
	s_waitcnt vmcnt(1)
	v_pk_fma_f32 v[2:3], v[134:135], v[66:67], v[2:3] op_sel_hi:[1,0,1]
	v_pk_fma_f32 v[0:1], v[132:133], v[66:67], v[0:1] op_sel_hi:[1,0,1]
	v_pk_fma_f32 v[6:7], v[134:135], v[74:75], v[6:7] op_sel_hi:[1,0,1]
	v_pk_fma_f32 v[4:5], v[132:133], v[74:75], v[4:5] op_sel_hi:[1,0,1]
	v_pk_fma_f32 v[10:11], v[134:135], v[82:83], v[10:11] op_sel_hi:[1,0,1]
	v_pk_fma_f32 v[8:9], v[132:133], v[82:83], v[8:9] op_sel_hi:[1,0,1]
	s_waitcnt vmcnt(0)
	v_pk_fma_f32 v[2:3], v[138:139], v[88:89], v[2:3] op_sel_hi:[1,0,1]
	v_pk_fma_f32 v[0:1], v[136:137], v[88:89], v[0:1] op_sel_hi:[1,0,1]
	v_pk_fma_f32 v[6:7], v[138:139], v[90:91], v[6:7] op_sel_hi:[1,0,1]
	v_pk_fma_f32 v[4:5], v[136:137], v[90:91], v[4:5] op_sel_hi:[1,0,1]
	v_pk_fma_f32 v[10:11], v[138:139], v[92:93], v[10:11] op_sel_hi:[1,0,1]
	v_pk_fma_f32 v[8:9], v[136:137], v[92:93], v[8:9] op_sel_hi:[1,0,1]
	s_and_saveexec_b64 s[10:11], s[4:5]
	s_cbranch_execz .LBB0_72
	ds_write_b128 v20, v[0:3] offset:49152
	ds_write_b128 v20, v[4:7] offset:50176
	ds_write_b128 v20, v[8:11] offset:51200
